# v21 + GEMM: first K iteration of every tile peeled with MFMA C=0, the 128 accumulator clears per tile are gone
# speedup vs baseline: 1.0127x; 1.0051x over previous
; #define PG8_STAGE(bufoff, gbase, voff) do { _Pragma("unroll") for (int _i = 0; _i < 2; ++_i) \
;         __builtin_amdgcn_global_load_lds((const unsigned*)((const char*)(gbase) + (voff)[_i]), (PG8_LAS unsigned*)(lds + (bufoff) + ldsw + _i * 8192), 16, 0, 0); } while (0)
; #define PG8_LDA(dst, b, h) do { _Pragma("unroll") for (int m = 0; m < 4; ++m) _Pragma("unroll") for (int k = 0; k < 2; ++k) dst[m][k] = *(const PG8_LAS bf16x8*)(lds + PG8_SA(b, h) + aoff + m * 2048 + k * 1024); } while (0)
; #define PG8_LDB(dst, b, h) do { _Pragma("unroll") for (int n = 0; n < 2; ++n) _Pragma("unroll") for (int k = 0; k < 2; ++k) dst[n][k] = *(const PG8_LAS bf16x8*)(lds + PG8_SB(b, h) + boff + n * 2048 + k * 1024); } while (0)
; #define PG8_MMA(ai, bj, At, Bt) do { __builtin_amdgcn_s_setprio(1); _Pragma("unroll") for (int m = 0; m < 4; ++m) _Pragma("unroll") for (int n = 0; n < 2; ++n) _Pragma("unroll") for (int k = 0; k < 2; ++k) \
;         acc[ai][bj][m][n] = __builtin_amdgcn_mfma_f32_16x16x32_bf16(Bt[n][k], At[m][k], acc[ai][bj][m][n], 0, 0, 0); __builtin_amdgcn_s_setprio(0); } while (0)
; #define PG8_WAIT_V(n) asm volatile("s_waitcnt vmcnt(" #n ")" ::: "memory")
; #define PG8_WAIT_L(n) asm volatile("s_waitcnt lgkmcnt(" #n ")" ::: "memory")
; #define PG8_BAR __builtin_amdgcn_s_barrier()
; #define PG8_SCHED __builtin_amdgcn_sched_barrier(0)
; template <class Epi, class Sched, bool ALIGN_EPI = false, bool SP2 = false>
; __device__ __forceinline__ void gemm_phase(PG8_LAS unsigned char* lds, const Gemm g, const Sched& S, const Epi& E) {
;     ...
;             if constexpr (SP2) {
;             PG8_LDB(B0, 0, 0); PG8_LDB(B1, 0, 1); PG8_SCHED; PG8_LDA(At, 0, 0); PG8_STAGE(PG8_SA(1, 1), a1 + hstep, voffA);
;             PG8_WAIT_V(8); PG8_WAIT_L(0); PG8_BAR; PG8_MMA(0, 0, At, B0); PG8_MMA(0, 1, At, B1); PG8_BAR; PG8_SCHED;
;             PG8_LDA(At, 0, 1); PG8_STAGE(PG8_SB(0, 0), b2, voffB); PG8_STAGE(PG8_SB(0, 1), b2 + hstep, voffB); PG8_STAGE(PG8_SA(0, 0), a2, voffA);
;     ...
; #pragma unroll
;         for (int a = 0; a < 2; ++a)
; #pragma unroll
;             for (int b = 0; b < 2; ++b)
; #pragma unroll
;                 for (int m = 0; m < 4; ++m)
; #pragma unroll
;                     for (int n = 0; n < 2; ++n) acc[a][b][m][n] = (f32x4){0.f, 0.f, 0.f, 0.f};
.LBB0_687:
	s_add_u32 s8, s8, 0x80
	s_addc_u32 s9, s9, 0
	s_add_u32 s27, s16, 0x100
	s_addc_u32 s30, s17, 0
	s_mov_b32 s16, 0
	s_waitcnt lgkmcnt(0)
	s_waitcnt lgkmcnt(0)
	s_add_i32 s31, s16, 2
	s_add_u32 s36, s8, 0x80
	s_addc_u32 s17, s9, 0
	s_add_i32 s41, 0, 0x10000
	s_cmp_eq_u32 s72, s16
	s_cselect_b32 s17, s1, s17
	s_cselect_b32 s16, s0, s36
	s_cselect_b32 vcc_hi, s93, s30
	s_cselect_b32 vcc_lo, s92, s27
	s_add_i32 s36, 0, 0x14000
	v_add_u32_e32 v152, s41, v161
	v_add_u32_e32 v178, s36, v161
	ds_read_b128 v[140:143], v152
	ds_read_b128 v[144:147], v152 offset:1024
	ds_read_b128 v[148:151], v152 offset:2048
	ds_read_b128 v[152:155], v152 offset:3072
	ds_read_b128 v[156:159], v178
	ds_read_b128 v[170:173], v178 offset:1024
	ds_read_b128 v[174:177], v178 offset:2048
	ds_read_b128 v[178:181], v178 offset:3072
	v_lshl_add_u64 v[210:211], s[8:9], 0, v[136:137]
	s_add_i32 m0, s76, 0xc000
	ds_read_b128 v[182:185], v169
	ds_read_b128 v[186:189], v169 offset:1024
	ds_read_b128 v[190:193], v169 offset:2048
	ds_read_b128 v[194:197], v169 offset:3072
	ds_read_b128 v[198:201], v169 offset:4096
	ds_read_b128 v[202:205], v169 offset:5120
	ds_read_b128 v[206:209], v169 offset:6144
	ds_read_b128 v[230:233], v169 offset:7168
	global_load_lds_dwordx4 v[210:211], off
	v_lshl_add_u64 v[210:211], s[8:9], 0, v[138:139]
	s_add_i32 m0, s76, 0xe000
	s_nop 0
	global_load_lds_dwordx4 v[210:211], off
	s_waitcnt vmcnt(8)
	s_waitcnt lgkmcnt(0)
	s_barrier
	s_setprio 1
	s_waitcnt lgkmcnt(0)
	v_mfma_f32_16x16x32_bf16 v[126:129], v[140:143], v[182:185], 0
	v_mfma_f32_16x16x32_bf16 v[122:125], v[148:151], v[182:185], 0
	v_mfma_f32_16x16x32_bf16 v[110:113], v[140:143], v[190:193], 0
	v_mfma_f32_16x16x32_bf16 v[106:109], v[148:151], v[190:193], 0
	v_mfma_f32_16x16x32_bf16 v[94:97], v[140:143], v[198:201], 0
	v_mfma_f32_16x16x32_bf16 v[90:93], v[148:151], v[198:201], 0
	v_mfma_f32_16x16x32_bf16 v[78:81], v[140:143], v[206:209], 0
	v_mfma_f32_16x16x32_bf16 v[74:77], v[148:151], v[206:209], 0
	v_mfma_f32_16x16x32_bf16 v[126:129], v[144:147], v[186:189], v[126:129]
	v_mfma_f32_16x16x32_bf16 v[122:125], v[152:155], v[186:189], v[122:125]
	v_mfma_f32_16x16x32_bf16 v[110:113], v[144:147], v[194:197], v[110:113]
	v_mfma_f32_16x16x32_bf16 v[106:109], v[152:155], v[194:197], v[106:109]
	v_mfma_f32_16x16x32_bf16 v[94:97], v[144:147], v[202:205], v[94:97]
	v_mfma_f32_16x16x32_bf16 v[90:93], v[152:155], v[202:205], v[90:93]
	v_mfma_f32_16x16x32_bf16 v[78:81], v[144:147], v[230:233], v[78:81]
	v_mfma_f32_16x16x32_bf16 v[74:77], v[152:155], v[230:233], v[74:77]
	s_setprio 0
	s_setprio 1
	v_mfma_f32_16x16x32_bf16 v[118:121], v[156:159], v[182:185], 0
	v_mfma_f32_16x16x32_bf16 v[114:117], v[174:177], v[182:185], 0
	v_mfma_f32_16x16x32_bf16 v[102:105], v[156:159], v[190:193], 0
	v_mfma_f32_16x16x32_bf16 v[98:101], v[174:177], v[190:193], 0
	v_mfma_f32_16x16x32_bf16 v[86:89], v[156:159], v[198:201], 0
	v_mfma_f32_16x16x32_bf16 v[82:85], v[174:177], v[198:201], 0
	v_mfma_f32_16x16x32_bf16 v[70:73], v[156:159], v[206:209], 0
	v_mfma_f32_16x16x32_bf16 v[66:69], v[174:177], v[206:209], 0
	v_mfma_f32_16x16x32_bf16 v[118:121], v[170:173], v[186:189], v[118:121]
	v_mfma_f32_16x16x32_bf16 v[114:117], v[178:181], v[186:189], v[114:117]
	v_mfma_f32_16x16x32_bf16 v[102:105], v[170:173], v[194:197], v[102:105]
	v_mfma_f32_16x16x32_bf16 v[98:101], v[178:181], v[194:197], v[98:101]
	v_mfma_f32_16x16x32_bf16 v[86:89], v[170:173], v[202:205], v[86:89]
	v_mfma_f32_16x16x32_bf16 v[82:85], v[178:181], v[202:205], v[82:85]
	v_mfma_f32_16x16x32_bf16 v[70:73], v[170:173], v[230:233], v[70:73]
	v_mfma_f32_16x16x32_bf16 v[66:69], v[178:181], v[230:233], v[66:69]
	s_setprio 0
	s_barrier
	s_add_i32 s41, s41, s65
	v_lshl_add_u64 v[210:211], vcc, 0, v[64:65]
	s_mov_b32 m0, s41
	ds_read_b128 v[182:185], v169 offset:16384
	ds_read_b128 v[186:189], v169 offset:17408
	ds_read_b128 v[190:193], v169 offset:18432
	ds_read_b128 v[194:197], v169 offset:19456
	ds_read_b128 v[198:201], v169 offset:20480
	ds_read_b128 v[202:205], v169 offset:21504
	ds_read_b128 v[206:209], v169 offset:22528
	ds_read_b128 v[230:233], v169 offset:23552
	global_load_lds_dwordx4 v[210:211], off
	s_add_i32 m0, s41, 0x2000
	v_lshl_add_u64 v[234:235], vcc, 0, v[134:135]
	s_add_u32 vcc_lo, vcc_lo, s4
	s_addc_u32 vcc_hi, vcc_hi, 0
	s_add_i32 s36, s36, s65
	global_load_lds_dwordx4 v[234:235], off
	v_lshl_add_u64 v[236:237], vcc, 0, v[64:65]
	s_mov_b32 m0, s36
	v_lshl_add_u64 v[238:239], vcc, 0, v[134:135]
	global_load_lds_dwordx4 v[236:237], off
	s_add_i32 m0, s36, 0x2000
	v_lshl_add_u64 v[244:245], s[16:17], 0, v[130:131]
	global_load_lds_dwordx4 v[238:239], off
	s_mov_b32 m0, s76
	v_lshl_add_u64 v[246:247], s[16:17], 0, v[132:133]
	global_load_lds_dwordx4 v[244:245], off
	s_mov_b32 m0, s2
	s_nop 0
	global_load_lds_dwordx4 v[246:247], off
	s_waitcnt vmcnt(8)
	s_waitcnt lgkmcnt(0)
	s_barrier
; #define PG8_STAGE(bufoff, gbase, voff) do { _Pragma("unroll") for (int _i = 0; _i < 2; ++_i) \
;         __builtin_amdgcn_global_load_lds((const unsigned*)((const char*)(gbase) + (voff)[_i]), (PG8_LAS unsigned*)(lds + (bufoff) + ldsw + _i * 8192), 16, 0, 0); } while (0)
; #define PG8_LDA(dst, b, h) do { _Pragma("unroll") for (int m = 0; m < 4; ++m) _Pragma("unroll") for (int k = 0; k < 2; ++k) dst[m][k] = *(const PG8_LAS bf16x8*)(lds + PG8_SA(b, h) + aoff + m * 2048 + k * 1024); } while (0)
; #define PG8_LDB(dst, b, h) do { _Pragma("unroll") for (int n = 0; n < 2; ++n) _Pragma("unroll") for (int k = 0; k < 2; ++k) dst[n][k] = *(const PG8_LAS bf16x8*)(lds + PG8_SB(b, h) + boff + n * 2048 + k * 1024); } while (0)
; #define PG8_MMA(ai, bj, At, Bt) do { __builtin_amdgcn_s_setprio(1); _Pragma("unroll") for (int m = 0; m < 4; ++m) _Pragma("unroll") for (int n = 0; n < 2; ++n) _Pragma("unroll") for (int k = 0; k < 2; ++k) \
;         acc[ai][bj][m][n] = __builtin_amdgcn_mfma_f32_16x16x32_bf16(Bt[n][k], At[m][k], acc[ai][bj][m][n], 0, 0, 0); __builtin_amdgcn_s_setprio(0); } while (0)
; #define PG8_WAIT_V(n) asm volatile("s_waitcnt vmcnt(" #n ")" ::: "memory")
; #define PG8_WAIT_L(n) asm volatile("s_waitcnt lgkmcnt(" #n ")" ::: "memory")
; #define PG8_BAR __builtin_amdgcn_s_barrier()
; #define PG8_SCHED __builtin_amdgcn_sched_barrier(0)
; template <class Epi, class Sched, bool ALIGN_EPI = false, bool SP2 = false>
; __device__ __forceinline__ void gemm_phase(PG8_LAS unsigned char* lds, const Gemm g, const Sched& S, const Epi& E) {
;     ...
;             PG8_WAIT_V(8); PG8_WAIT_L(0); PG8_BAR; PG8_MMA(1, 0, At, B0); PG8_MMA(1, 1, At, B1); PG8_BAR; PG8_SCHED;
;             PG8_LDB(B0, 1, 0); PG8_LDB(B1, 1, 1); PG8_SCHED; PG8_LDA(At, 1, 0); PG8_STAGE(PG8_SA(0, 1), a2 + hstep, voffA);
;             PG8_WAIT_V(8); PG8_WAIT_L(0); PG8_BAR; PG8_MMA(0, 0, At, B0); PG8_MMA(0, 1, At, B1); PG8_BAR; PG8_SCHED;
	s_setprio 1
	s_waitcnt lgkmcnt(0)
	v_mfma_f32_16x16x32_bf16 v[60:63], v[140:143], v[182:185], 0
	v_mfma_f32_16x16x32_bf16 v[56:59], v[148:151], v[182:185], 0
	v_mfma_f32_16x16x32_bf16 v[44:47], v[140:143], v[190:193], 0
	v_mfma_f32_16x16x32_bf16 v[40:43], v[148:151], v[190:193], 0
	v_mfma_f32_16x16x32_bf16 v[28:31], v[140:143], v[198:201], 0
	v_mfma_f32_16x16x32_bf16 v[24:27], v[148:151], v[198:201], 0
	v_mfma_f32_16x16x32_bf16 v[12:15], v[140:143], v[206:209], 0
	v_mfma_f32_16x16x32_bf16 v[8:11], v[148:151], v[206:209], 0
	v_mfma_f32_16x16x32_bf16 v[60:63], v[144:147], v[186:189], v[60:63]
	v_mfma_f32_16x16x32_bf16 v[56:59], v[152:155], v[186:189], v[56:59]
	v_mfma_f32_16x16x32_bf16 v[44:47], v[144:147], v[194:197], v[44:47]
	v_mfma_f32_16x16x32_bf16 v[40:43], v[152:155], v[194:197], v[40:43]
	v_mfma_f32_16x16x32_bf16 v[28:31], v[144:147], v[202:205], v[28:31]
	v_mfma_f32_16x16x32_bf16 v[24:27], v[152:155], v[202:205], v[24:27]
	v_mfma_f32_16x16x32_bf16 v[12:15], v[144:147], v[230:233], v[12:15]
	v_mfma_f32_16x16x32_bf16 v[8:11], v[152:155], v[230:233], v[8:11]
	s_setprio 0
	s_setprio 1
	v_mfma_f32_16x16x32_bf16 v[52:55], v[156:159], v[182:185], 0
	v_mfma_f32_16x16x32_bf16 v[48:51], v[174:177], v[182:185], 0
	v_mfma_f32_16x16x32_bf16 v[36:39], v[156:159], v[190:193], 0
	v_mfma_f32_16x16x32_bf16 v[32:35], v[174:177], v[190:193], 0
	v_mfma_f32_16x16x32_bf16 v[20:23], v[156:159], v[198:201], 0
	v_mfma_f32_16x16x32_bf16 v[16:19], v[174:177], v[198:201], 0
	v_mfma_f32_16x16x32_bf16 v[4:7], v[156:159], v[206:209], 0
	v_mfma_f32_16x16x32_bf16 v[0:3], v[174:177], v[206:209], 0
	v_mfma_f32_16x16x32_bf16 v[52:55], v[170:173], v[186:189], v[52:55]
	v_mfma_f32_16x16x32_bf16 v[48:51], v[178:181], v[186:189], v[48:51]
	v_mfma_f32_16x16x32_bf16 v[36:39], v[170:173], v[194:197], v[36:39]
	v_mfma_f32_16x16x32_bf16 v[32:35], v[178:181], v[194:197], v[32:35]
	v_mfma_f32_16x16x32_bf16 v[20:23], v[170:173], v[202:205], v[20:23]
	v_mfma_f32_16x16x32_bf16 v[16:19], v[178:181], v[202:205], v[16:19]
	v_mfma_f32_16x16x32_bf16 v[4:7], v[170:173], v[230:233], v[4:7]
	v_mfma_f32_16x16x32_bf16 v[0:3], v[178:181], v[230:233], v[0:3]
	s_setprio 0
	s_barrier
	s_add_i32 s36, 0, 0x18000
	s_add_i32 s41, 0, 0x1c000
	v_add_u32_e32 v152, s36, v161
	v_add_u32_e32 v178, s41, v161
	ds_read_b128 v[140:143], v152
	ds_read_b128 v[144:147], v152 offset:1024
	ds_read_b128 v[148:151], v152 offset:2048
	ds_read_b128 v[152:155], v152 offset:3072
	ds_read_b128 v[156:159], v178
	ds_read_b128 v[170:173], v178 offset:1024
	ds_read_b128 v[174:177], v178 offset:2048
	ds_read_b128 v[178:181], v178 offset:3072
	s_add_u32 s16, s16, s4
	s_addc_u32 s17, s17, 0
	s_mov_b32 m0, s3
	v_lshl_add_u64 v[248:249], s[16:17], 0, v[130:131]
	ds_read_b128 v[182:185], v169 offset:32768
	ds_read_b128 v[186:189], v169 offset:33792
	ds_read_b128 v[190:193], v169 offset:34816
	ds_read_b128 v[194:197], v169 offset:35840
	ds_read_b128 v[198:201], v169 offset:36864
	ds_read_b128 v[202:205], v169 offset:37888
	ds_read_b128 v[206:209], v169 offset:38912
	ds_read_b128 v[230:233], v169 offset:39936
	global_load_lds_dwordx4 v[248:249], off
	v_lshl_add_u64 v[248:249], s[16:17], 0, v[132:133]
	s_mov_b32 m0, s70
	s_nop 0
	global_load_lds_dwordx4 v[248:249], off
	s_waitcnt vmcnt(8)
	s_waitcnt lgkmcnt(0)
	s_barrier
	s_setprio 1
	s_waitcnt lgkmcnt(0)
	v_mfma_f32_16x16x32_bf16 v[126:129], v[140:143], v[182:185], v[126:129]
	v_mfma_f32_16x16x32_bf16 v[122:125], v[148:151], v[182:185], v[122:125]
	v_mfma_f32_16x16x32_bf16 v[110:113], v[140:143], v[190:193], v[110:113]
	v_mfma_f32_16x16x32_bf16 v[106:109], v[148:151], v[190:193], v[106:109]
	v_mfma_f32_16x16x32_bf16 v[94:97], v[140:143], v[198:201], v[94:97]
	v_mfma_f32_16x16x32_bf16 v[90:93], v[148:151], v[198:201], v[90:93]
	v_mfma_f32_16x16x32_bf16 v[78:81], v[140:143], v[206:209], v[78:81]
	v_mfma_f32_16x16x32_bf16 v[74:77], v[148:151], v[206:209], v[74:77]
	v_mfma_f32_16x16x32_bf16 v[126:129], v[144:147], v[186:189], v[126:129]
	v_mfma_f32_16x16x32_bf16 v[122:125], v[152:155], v[186:189], v[122:125]
	v_mfma_f32_16x16x32_bf16 v[110:113], v[144:147], v[194:197], v[110:113]
	v_mfma_f32_16x16x32_bf16 v[106:109], v[152:155], v[194:197], v[106:109]
	v_mfma_f32_16x16x32_bf16 v[94:97], v[144:147], v[202:205], v[94:97]
	v_mfma_f32_16x16x32_bf16 v[90:93], v[152:155], v[202:205], v[90:93]
	v_mfma_f32_16x16x32_bf16 v[78:81], v[144:147], v[230:233], v[78:81]
	v_mfma_f32_16x16x32_bf16 v[74:77], v[152:155], v[230:233], v[74:77]
	s_setprio 0
	s_setprio 1
	v_mfma_f32_16x16x32_bf16 v[118:121], v[156:159], v[182:185], v[118:121]
	v_mfma_f32_16x16x32_bf16 v[114:117], v[174:177], v[182:185], v[114:117]
	v_mfma_f32_16x16x32_bf16 v[102:105], v[156:159], v[190:193], v[102:105]
	v_mfma_f32_16x16x32_bf16 v[98:101], v[174:177], v[190:193], v[98:101]
	v_mfma_f32_16x16x32_bf16 v[86:89], v[156:159], v[198:201], v[86:89]
	v_mfma_f32_16x16x32_bf16 v[82:85], v[174:177], v[198:201], v[82:85]
	v_mfma_f32_16x16x32_bf16 v[70:73], v[156:159], v[206:209], v[70:73]
	v_mfma_f32_16x16x32_bf16 v[66:69], v[174:177], v[206:209], v[66:69]
	v_mfma_f32_16x16x32_bf16 v[118:121], v[170:173], v[186:189], v[118:121]
	v_mfma_f32_16x16x32_bf16 v[114:117], v[178:181], v[186:189], v[114:117]
	v_mfma_f32_16x16x32_bf16 v[102:105], v[170:173], v[194:197], v[102:105]
	v_mfma_f32_16x16x32_bf16 v[98:101], v[178:181], v[194:197], v[98:101]
	v_mfma_f32_16x16x32_bf16 v[86:89], v[170:173], v[202:205], v[86:89]
	v_mfma_f32_16x16x32_bf16 v[82:85], v[178:181], v[202:205], v[82:85]
	v_mfma_f32_16x16x32_bf16 v[70:73], v[170:173], v[230:233], v[70:73]
	v_mfma_f32_16x16x32_bf16 v[66:69], v[178:181], v[230:233], v[66:69]
	s_setprio 0
	s_barrier
; #define PG8_STAGE(bufoff, gbase, voff) do { _Pragma("unroll") for (int _i = 0; _i < 2; ++_i) \
;         __builtin_amdgcn_global_load_lds((const unsigned*)((const char*)(gbase) + (voff)[_i]), (PG8_LAS unsigned*)(lds + (bufoff) + ldsw + _i * 8192), 16, 0, 0); } while (0)
; #define PG8_LDA(dst, b, h) do { _Pragma("unroll") for (int m = 0; m < 4; ++m) _Pragma("unroll") for (int k = 0; k < 2; ++k) dst[m][k] = *(const PG8_LAS bf16x8*)(lds + PG8_SA(b, h) + aoff + m * 2048 + k * 1024); } while (0)
; #define PG8_MMA(ai, bj, At, Bt) do { __builtin_amdgcn_s_setprio(1); _Pragma("unroll") for (int m = 0; m < 4; ++m) _Pragma("unroll") for (int n = 0; n < 2; ++n) _Pragma("unroll") for (int k = 0; k < 2; ++k) \
;         acc[ai][bj][m][n] = __builtin_amdgcn_mfma_f32_16x16x32_bf16(Bt[n][k], At[m][k], acc[ai][bj][m][n], 0, 0, 0); __builtin_amdgcn_s_setprio(0); } while (0)
; #define PG8_WAIT_V(n) asm volatile("s_waitcnt vmcnt(" #n ")" ::: "memory")
; #define PG8_WAIT_L(n) asm volatile("s_waitcnt lgkmcnt(" #n ")" ::: "memory")
; #define PG8_BAR __builtin_amdgcn_s_barrier()
; #define PG8_SCHED __builtin_amdgcn_sched_barrier(0)
; template <class Epi, class Sched, bool ALIGN_EPI = false, bool SP2 = false>
; __device__ __forceinline__ void gemm_phase(PG8_LAS unsigned char* lds, const Gemm g, const Sched& S, const Epi& E) {
;     ...
;         for (int t = 0; t < nt; t += 2) {
;             const bool last = (t == nt - 2);
;             const char* a1 = cA + (size_t)(t + 1) * kstep;
;             const char* a2 = last ? nA : cA + (size_t)(t + 2) * kstep; const char* b2 = last ? nB : cB + (size_t)(t + 2) * kstep;
;             const char* a3 = a2 + kstep; const char* b3 = b2 + kstep;
;     ...
;             PG8_LDA(At, 1, 1); PG8_STAGE(PG8_SB(1, 0), b3, voffB); PG8_STAGE(PG8_SB(1, 1), b3 + hstep, voffB); PG8_STAGE(PG8_SA(1, 0), a3, voffA);
;             PG8_WAIT_V(8); PG8_WAIT_L(0); PG8_BAR; PG8_MMA(1, 0, At, B0); PG8_MMA(1, 1, At, B1); PG8_BAR; PG8_SCHED;
	s_add_i32 s16, s36, s65
	v_lshl_add_u64 v[210:211], v[210:211], 0, s[44:45]
	s_mov_b32 m0, s16
	ds_read_b128 v[182:185], v169 offset:49152
	ds_read_b128 v[186:189], v169 offset:50176
	ds_read_b128 v[190:193], v169 offset:51200
	ds_read_b128 v[194:197], v169 offset:52224
	ds_read_b128 v[198:201], v169 offset:53248
	ds_read_b128 v[202:205], v169 offset:54272
	ds_read_b128 v[206:209], v169 offset:55296
	ds_read_b128 v[230:233], v169 offset:56320
	global_load_lds_dwordx4 v[210:211], off
	v_lshl_add_u64 v[210:211], v[234:235], 0, s[44:45]
	s_add_i32 m0, s16, 0x2000
	s_add_i32 s16, s41, s65
	global_load_lds_dwordx4 v[210:211], off
	v_lshl_add_u64 v[210:211], v[236:237], 0, s[44:45]
	s_mov_b32 m0, s16
	s_nop 0
	global_load_lds_dwordx4 v[210:211], off
	v_lshl_add_u64 v[210:211], v[238:239], 0, s[44:45]
	s_add_i32 m0, s16, 0x2000
	s_nop 0
	global_load_lds_dwordx4 v[210:211], off
	v_lshl_add_u64 v[210:211], v[244:245], 0, s[44:45]
	s_mov_b32 m0, s73
	s_nop 0
	global_load_lds_dwordx4 v[210:211], off
	v_lshl_add_u64 v[210:211], v[246:247], 0, s[44:45]
	s_mov_b32 m0, s68
	s_nop 0
	global_load_lds_dwordx4 v[210:211], off
	s_waitcnt vmcnt(8)
	s_waitcnt lgkmcnt(0)
	s_barrier
	s_setprio 1
	s_waitcnt lgkmcnt(0)
	v_mfma_f32_16x16x32_bf16 v[60:63], v[140:143], v[182:185], v[60:63]
	v_mfma_f32_16x16x32_bf16 v[56:59], v[148:151], v[182:185], v[56:59]
	v_mfma_f32_16x16x32_bf16 v[44:47], v[140:143], v[190:193], v[44:47]
	v_mfma_f32_16x16x32_bf16 v[40:43], v[148:151], v[190:193], v[40:43]
	v_mfma_f32_16x16x32_bf16 v[28:31], v[140:143], v[198:201], v[28:31]
	v_mfma_f32_16x16x32_bf16 v[24:27], v[148:151], v[198:201], v[24:27]
	v_mfma_f32_16x16x32_bf16 v[12:15], v[140:143], v[206:209], v[12:15]
	v_mfma_f32_16x16x32_bf16 v[8:11], v[148:151], v[206:209], v[8:11]
	v_mfma_f32_16x16x32_bf16 v[60:63], v[144:147], v[186:189], v[60:63]
	v_mfma_f32_16x16x32_bf16 v[56:59], v[152:155], v[186:189], v[56:59]
	v_mfma_f32_16x16x32_bf16 v[44:47], v[144:147], v[194:197], v[44:47]
	v_mfma_f32_16x16x32_bf16 v[40:43], v[152:155], v[194:197], v[40:43]
	v_mfma_f32_16x16x32_bf16 v[28:31], v[144:147], v[202:205], v[28:31]
	v_mfma_f32_16x16x32_bf16 v[24:27], v[152:155], v[202:205], v[24:27]
	v_mfma_f32_16x16x32_bf16 v[12:15], v[144:147], v[230:233], v[12:15]
	v_mfma_f32_16x16x32_bf16 v[8:11], v[152:155], v[230:233], v[8:11]
	s_setprio 0
	s_setprio 1
	v_mfma_f32_16x16x32_bf16 v[52:55], v[156:159], v[182:185], v[52:55]
	v_mfma_f32_16x16x32_bf16 v[48:51], v[174:177], v[182:185], v[48:51]
	v_mfma_f32_16x16x32_bf16 v[36:39], v[156:159], v[190:193], v[36:39]
	v_mfma_f32_16x16x32_bf16 v[32:35], v[174:177], v[190:193], v[32:35]
	v_mfma_f32_16x16x32_bf16 v[20:23], v[156:159], v[198:201], v[20:23]
	v_mfma_f32_16x16x32_bf16 v[16:19], v[174:177], v[198:201], v[16:19]
	v_mfma_f32_16x16x32_bf16 v[4:7], v[156:159], v[206:209], v[4:7]
	v_mfma_f32_16x16x32_bf16 v[0:3], v[174:177], v[206:209], v[0:3]
	v_mfma_f32_16x16x32_bf16 v[52:55], v[170:173], v[186:189], v[52:55]
	v_mfma_f32_16x16x32_bf16 v[48:51], v[178:181], v[186:189], v[48:51]
	v_mfma_f32_16x16x32_bf16 v[36:39], v[170:173], v[194:197], v[36:39]
	v_mfma_f32_16x16x32_bf16 v[32:35], v[178:181], v[194:197], v[32:35]
	v_mfma_f32_16x16x32_bf16 v[20:23], v[170:173], v[202:205], v[20:23]
	v_mfma_f32_16x16x32_bf16 v[16:19], v[178:181], v[202:205], v[16:19]
	v_mfma_f32_16x16x32_bf16 v[4:7], v[170:173], v[230:233], v[4:7]
	v_mfma_f32_16x16x32_bf16 v[0:3], v[178:181], v[230:233], v[0:3]
	s_setprio 0
	s_barrier
	s_add_u32 s8, s8, 0x100
	s_addc_u32 s9, s9, 0
	s_add_u32 s27, s27, 0x100
	s_addc_u32 s30, s30, 0
	s_cmp_ge_u32 s31, s87
	s_mov_b32 s16, s31
	s_cbranch_scc0 .LBB0_688
	s_branch .Lk_loop_done

; #define PG8_BAR __builtin_amdgcn_s_barrier()
; template <class Epi, class Sched, bool ALIGN_EPI = false, bool SP2 = false>
; __device__ __forceinline__ void gemm_phase(PG8_LAS unsigned char* lds, const Gemm g, const Sched& S, const Epi& E) {
;     ...
;         if constexpr (ALIGN_EPI) { if (wr == 0) PG8_BAR; }
;         if constexpr (!Epi::AFTER_DRAIN) { E(acc, cur, wr, wc, fr, fq); S.done(cur); }
.Lk_loop_done:
	s_and_b64 vcc, exec, s[94:95]
	s_cbranch_vccz .LBB0_691
	s_barrier
